# static priority: one s_setprio 1 for waves 0-3 (wr=0 half) per GEMM phase, per-block flips deleted; on top of chain+prep3+novalu
# speedup vs baseline: 1.0042x; 1.0002x over previous
; #define PG8_BAR __builtin_amdgcn_s_barrier()
; template <class Epi, class Sched, bool ALIGN_EPI = false, bool SP2 = false>
; __device__ __forceinline__ void gemm_phase(PG8_LAS unsigned char* lds, const Gemm g, const Sched& S, const Epi& E) {
;     ...
;         if (wr == 1) PG8_BAR;
.LBB0_197:
	s_cmp_lg_u32 s6, 1
	s_cbranch_scc0 .Lprio_skip_0
	s_setprio 1

; #define PG8_BAR __builtin_amdgcn_s_barrier()
; template <class Epi, class Sched, bool ALIGN_EPI = false, bool SP2 = false>
; __device__ __forceinline__ void gemm_phase(PG8_LAS unsigned char* lds, const Gemm g, const Sched& S, const Epi& E) {
;     ...
;         if (wr == 1) PG8_BAR;
.LBB0_609:
	s_cmp_lg_u32 s3, 1
	s_cbranch_scc0 .Lprio_skip_1
	s_setprio 1
